# P6 in-loop copy block issued inside phase 0's MFMA burst (vmcnt windows 8/10/10/8) instead of in the load segment
# speedup vs baseline: 1.0071x; 1.0071x over previous
.LBB0_740:
	ds_read_b128 v[44:47], v205
	ds_read_b128 v[48:51], v205 offset:1024
	ds_read_b128 v[52:55], v205 offset:2048
	ds_read_b128 v[56:59], v205 offset:3072
	ds_read_b128 v[60:63], v206
	ds_read_b128 v[64:67], v206 offset:1024
	ds_read_b128 v[68:71], v206 offset:2048
	ds_read_b128 v[160:163], v206 offset:3072
	s_add_u32 s12, s10, s8
	s_addc_u32 s13, s11, s9
	s_add_u32 s12, s12, 0x100
	s_addc_u32 s13, s13, 0
	s_add_u32 s63, s19, s8
	s_addc_u32 vcc_lo, s55, s9
	s_cmpk_eq_i32 s8, 0x700
	s_cselect_b32 s15, s59, s13
	s_cselect_b32 s14, s58, s12
	s_cselect_b32 s4, s57, s1
	s_cselect_b32 s5, s56, s0
	s_cselect_b32 s13, s3, vcc_lo
	s_cselect_b32 s12, s18, s63
	s_cselect_b32 s63, s97, s17
	v_lshl_add_u64 v[224:225], v[42:43], 0, s[8:9]
	s_add_i32 m0, s65, 0xc000
	ds_read_b128 v[164:167], v207
	ds_read_b128 v[168:171], v207 offset:1024
	ds_read_b128 v[172:175], v207 offset:2048
	ds_read_b128 v[194:197], v207 offset:3072
	ds_read_b128 v[198:201], v207 offset:4096
	ds_read_b128 v[210:213], v207 offset:5120
	ds_read_b128 v[214:217], v207 offset:6144
	ds_read_b128 v[218:221], v207 offset:7168
	global_load_lds_dwordx4 v[224:225], off
	v_lshl_add_u64 v[224:225], v[40:41], 0, s[8:9]
	s_add_i32 m0, s65, 0xe000
	s_nop 0
	global_load_lds_dwordx4 v[224:225], off
	s_waitcnt vmcnt(8)
	s_waitcnt lgkmcnt(0)
	s_barrier
	s_setprio 1
	s_waitcnt lgkmcnt(0)
	v_mfma_f32_16x16x32_bf16 v[156:159], v[44:47], v[164:167], v[156:159]
	v_mfma_f32_16x16x32_bf16 v[152:155], v[52:55], v[164:167], v[152:155]
	v_mfma_f32_16x16x32_bf16 v[140:143], v[44:47], v[172:175], v[140:143]
	v_mfma_f32_16x16x32_bf16 v[136:139], v[52:55], v[172:175], v[136:139]
	v_mfma_f32_16x16x32_bf16 v[124:127], v[44:47], v[198:201], v[124:127]
	v_mfma_f32_16x16x32_bf16 v[120:123], v[52:55], v[198:201], v[120:123]
	v_readlane_b32 s32, v247, 60
	s_add_i32 s32, s32, -1
	v_readlane_b32 s100, v247, 61
	s_min_u32 s32, s32, s100
	v_readlane_b32 s100, v247, 62
	s_add_i32 s32, s32, s100
	s_min_u32 s32, s32, 0x2f6f
	s_lshr_b32 s100, s32, 1
	s_add_i32 s100, s100, 0x2808
	s_mul_i32 s101, s100, 0x8081
	s_lshr_b32 s101, s101, 24
	s_mul_i32 s98, s101, 0x1fe
	s_sub_i32 s100, s100, s98
	s_lshl_b32 s101, s101, 22
	s_lshl_b32 s100, s100, 13
	s_add_u32 s100, s100, s101
	s_bitcmp1_b32 s32, 0
	s_cselect_b32 s98, s66, s70
	s_cselect_b32 s99, s67, s71
	s_add_u32 s98, s98, s100
	s_addc_u32 s99, s99, 0
	v_lshlrev_b32_e32 v236, 4, v222
	global_store_dwordx4 v236, v[252:255], s[98:99] nt
	v_readlane_b32 s32, v247, 60
	v_readlane_b32 s100, v247, 61
	s_min_u32 s32, s32, s100
	v_readlane_b32 s100, v247, 62
	s_add_i32 s32, s32, s100
	s_min_u32 s32, s32, 0x2f6f
	s_lshr_b32 s100, s32, 1
	s_add_i32 s100, s100, 0x2808
	s_mul_i32 s101, s100, 0x8081
	s_lshr_b32 s101, s101, 24
	s_mul_i32 s98, s101, 0x1fe
	s_sub_i32 s100, s100, s98
	s_lshl_b32 s101, s101, 22
	s_lshl_b32 s100, s100, 13
	s_add_u32 s100, s100, s101
	s_bitcmp1_b32 s32, 0
	s_cselect_b32 s98, s84, s82
	s_cselect_b32 s99, s85, s83
	s_add_u32 s98, s98, s100
	s_addc_u32 s99, s99, 0
	s_add_u32 s98, s98, 0x4000
	s_addc_u32 s99, s99, 0
	v_lshlrev_b32_e32 v236, 4, v222
	global_load_dwordx4 v[252:255], v236, s[98:99] nt
	v_readlane_b32 s32, v247, 60
	s_add_i32 s32, s32, 1
	v_writelane_b32 v247, s32, 60
	s_nop 0
	v_mfma_f32_16x16x32_bf16 v[108:111], v[44:47], v[214:217], v[108:111]
	v_mfma_f32_16x16x32_bf16 v[104:107], v[52:55], v[214:217], v[104:107]
	v_mfma_f32_16x16x32_bf16 v[156:159], v[48:51], v[168:171], v[156:159]
	v_mfma_f32_16x16x32_bf16 v[152:155], v[56:59], v[168:171], v[152:155]
	v_mfma_f32_16x16x32_bf16 v[140:143], v[48:51], v[194:197], v[140:143]
	v_mfma_f32_16x16x32_bf16 v[136:139], v[56:59], v[194:197], v[136:139]
	v_mfma_f32_16x16x32_bf16 v[124:127], v[48:51], v[210:213], v[124:127]
	v_mfma_f32_16x16x32_bf16 v[120:123], v[56:59], v[210:213], v[120:123]
	v_mfma_f32_16x16x32_bf16 v[108:111], v[48:51], v[218:221], v[108:111]
	v_mfma_f32_16x16x32_bf16 v[104:107], v[56:59], v[218:221], v[104:107]
	s_setprio 0
	s_setprio 1
	v_mfma_f32_16x16x32_bf16 v[148:151], v[60:63], v[164:167], v[148:151]
	v_mfma_f32_16x16x32_bf16 v[144:147], v[68:71], v[164:167], v[144:147]
	v_mfma_f32_16x16x32_bf16 v[132:135], v[60:63], v[172:175], v[132:135]
	v_mfma_f32_16x16x32_bf16 v[128:131], v[68:71], v[172:175], v[128:131]
	v_mfma_f32_16x16x32_bf16 v[116:119], v[60:63], v[198:201], v[116:119]
	v_mfma_f32_16x16x32_bf16 v[112:115], v[68:71], v[198:201], v[112:115]
	v_mfma_f32_16x16x32_bf16 v[100:103], v[60:63], v[214:217], v[100:103]
	v_mfma_f32_16x16x32_bf16 v[96:99], v[68:71], v[214:217], v[96:99]
	v_mfma_f32_16x16x32_bf16 v[148:151], v[64:67], v[168:171], v[148:151]
	v_mfma_f32_16x16x32_bf16 v[144:147], v[160:163], v[168:171], v[144:147]
	v_mfma_f32_16x16x32_bf16 v[132:135], v[64:67], v[194:197], v[132:135]
	v_mfma_f32_16x16x32_bf16 v[128:131], v[160:163], v[194:197], v[128:131]
	v_mfma_f32_16x16x32_bf16 v[116:119], v[64:67], v[210:213], v[116:119]
	v_mfma_f32_16x16x32_bf16 v[112:115], v[160:163], v[210:213], v[112:115]
	v_mfma_f32_16x16x32_bf16 v[100:103], v[64:67], v[218:221], v[100:103]
	v_mfma_f32_16x16x32_bf16 v[96:99], v[160:163], v[218:221], v[96:99]
	s_setprio 0
	s_barrier
	s_add_i32 vcc_lo, s88, s33
	v_lshl_add_u64 v[228:229], s[12:13], 0, v[178:179]
	s_mov_b32 m0, vcc_lo
	ds_read_b128 v[164:167], v207 offset:16384
	ds_read_b128 v[168:171], v207 offset:17408
	ds_read_b128 v[172:175], v207 offset:18432
	ds_read_b128 v[194:197], v207 offset:19456
	ds_read_b128 v[198:201], v207 offset:20480
	ds_read_b128 v[210:213], v207 offset:21504
	ds_read_b128 v[214:217], v207 offset:22528
	ds_read_b128 v[218:221], v207 offset:23552
	global_load_lds_dwordx4 v[228:229], off
	s_add_i32 m0, vcc_lo, 0x2000
	s_add_u32 vcc_lo, s12, 0x40000
	v_lshl_add_u64 v[230:231], s[12:13], 0, v[182:183]
	s_addc_u32 vcc_hi, s13, 0
	s_add_i32 s36, s89, s33
	global_load_lds_dwordx4 v[230:231], off
	v_lshl_add_u64 v[224:225], vcc, 0, v[178:179]
	s_mov_b32 m0, s36
	v_lshl_add_u64 v[232:233], s[14:15], 0, v[176:177]
	global_load_lds_dwordx4 v[224:225], off
	s_add_i32 m0, s36, 0x2000
	v_lshl_add_u64 v[224:225], vcc, 0, v[182:183]
	s_sub_u32 vcc_lo, 0, s63
	global_load_lds_dwordx4 v[224:225], off
	s_mov_b32 m0, s65
	v_lshl_add_u64 v[224:225], s[14:15], 0, v[180:181]
	s_subb_u32 vcc_hi, 0, 0
	global_load_lds_dwordx4 v[232:233], off
	v_lshl_add_u64 v[234:235], v[224:225], 0, vcc
	s_mov_b32 m0, s68
	s_nop 0
	global_load_lds_dwordx4 v[234:235], off
	s_waitcnt vmcnt(10)
	s_waitcnt lgkmcnt(0)
	s_barrier
	s_setprio 1
	s_waitcnt lgkmcnt(0)
	v_mfma_f32_16x16x32_bf16 v[92:95], v[44:47], v[164:167], v[92:95]
	v_mfma_f32_16x16x32_bf16 v[88:91], v[52:55], v[164:167], v[88:91]
	v_mfma_f32_16x16x32_bf16 v[76:79], v[44:47], v[172:175], v[76:79]
	v_mfma_f32_16x16x32_bf16 v[72:75], v[52:55], v[172:175], v[72:75]
	v_mfma_f32_16x16x32_bf16 v[28:31], v[44:47], v[198:201], v[28:31]
	v_mfma_f32_16x16x32_bf16 v[24:27], v[52:55], v[198:201], v[24:27]
	v_mfma_f32_16x16x32_bf16 v[12:15], v[44:47], v[214:217], v[12:15]
	v_mfma_f32_16x16x32_bf16 v[8:11], v[52:55], v[214:217], v[8:11]
	v_mfma_f32_16x16x32_bf16 v[92:95], v[48:51], v[168:171], v[92:95]
	v_mfma_f32_16x16x32_bf16 v[88:91], v[56:59], v[168:171], v[88:91]
	v_mfma_f32_16x16x32_bf16 v[76:79], v[48:51], v[194:197], v[76:79]
	v_mfma_f32_16x16x32_bf16 v[72:75], v[56:59], v[194:197], v[72:75]
	v_mfma_f32_16x16x32_bf16 v[28:31], v[48:51], v[210:213], v[28:31]
	v_mfma_f32_16x16x32_bf16 v[24:27], v[56:59], v[210:213], v[24:27]
	v_mfma_f32_16x16x32_bf16 v[12:15], v[48:51], v[218:221], v[12:15]
	v_mfma_f32_16x16x32_bf16 v[8:11], v[56:59], v[218:221], v[8:11]
	s_setprio 0
	s_setprio 1
	v_mfma_f32_16x16x32_bf16 v[36:39], v[60:63], v[172:175], v[36:39]
	v_mfma_f32_16x16x32_bf16 v[32:35], v[68:71], v[172:175], v[32:35]
	v_mfma_f32_16x16x32_bf16 v[20:23], v[60:63], v[198:201], v[20:23]
	v_mfma_f32_16x16x32_bf16 v[16:19], v[68:71], v[198:201], v[16:19]
	v_mfma_f32_16x16x32_bf16 v[4:7], v[60:63], v[214:217], v[4:7]
	v_mfma_f32_16x16x32_bf16 v[0:3], v[68:71], v[214:217], v[0:3]
	v_mfma_f32_16x16x32_bf16 v[44:47], v[60:63], v[164:167], v[84:87]
	v_mfma_f32_16x16x32_bf16 v[48:51], v[68:71], v[164:167], v[80:83]
	v_mfma_f32_16x16x32_bf16 v[36:39], v[64:67], v[194:197], v[36:39]
	v_mfma_f32_16x16x32_bf16 v[32:35], v[160:163], v[194:197], v[32:35]
	v_mfma_f32_16x16x32_bf16 v[20:23], v[64:67], v[210:213], v[20:23]
	v_mfma_f32_16x16x32_bf16 v[16:19], v[160:163], v[210:213], v[16:19]
	v_mfma_f32_16x16x32_bf16 v[4:7], v[64:67], v[218:221], v[4:7]
	v_mfma_f32_16x16x32_bf16 v[0:3], v[160:163], v[218:221], v[0:3]
	v_mfma_f32_16x16x32_bf16 v[44:47], v[64:67], v[168:171], v[44:47]
	v_mfma_f32_16x16x32_bf16 v[48:51], v[160:163], v[168:171], v[48:51]
	s_setprio 0
	s_barrier
	s_add_i32 s36, 0, 0x18000
	s_add_i32 s37, 0, 0x1c000
	v_add_u32_e32 v64, s36, v204
	v_add_u32_e32 v80, s37, v204
	ds_read_b128 v[52:55], v64
	ds_read_b128 v[56:59], v64 offset:1024
	ds_read_b128 v[60:63], v64 offset:2048
	ds_read_b128 v[64:67], v64 offset:3072
	ds_read_b128 v[68:71], v80
	ds_read_b128 v[160:163], v80 offset:1024
	ds_read_b128 v[164:167], v80 offset:2048
	ds_read_b128 v[168:171], v80 offset:3072
	s_add_u32 s14, s14, s5
	s_addc_u32 s15, s15, s4
	s_mov_b32 m0, s69
	v_lshl_add_u64 v[224:225], s[14:15], 0, v[176:177]
	ds_read_b128 v[80:83], v207 offset:32768
	ds_read_b128 v[84:87], v207 offset:33792
	ds_read_b128 v[172:175], v207 offset:34816
	ds_read_b128 v[194:197], v207 offset:35840
	ds_read_b128 v[198:201], v207 offset:36864
	ds_read_b128 v[210:213], v207 offset:37888
	ds_read_b128 v[214:217], v207 offset:38912
	ds_read_b128 v[218:221], v207 offset:39936
	global_load_lds_dwordx4 v[224:225], off
	v_lshl_add_u64 v[224:225], s[14:15], 0, v[180:181]
	v_lshl_add_u64 v[224:225], v[224:225], 0, vcc
	s_mov_b32 m0, s72
	s_nop 0
	global_load_lds_dwordx4 v[224:225], off
	s_waitcnt vmcnt(10)
	s_waitcnt lgkmcnt(0)
	s_barrier
	s_setprio 1
	s_waitcnt lgkmcnt(0)
	v_mfma_f32_16x16x32_bf16 v[156:159], v[52:55], v[80:83], v[156:159]
	v_mfma_f32_16x16x32_bf16 v[152:155], v[60:63], v[80:83], v[152:155]
	v_mfma_f32_16x16x32_bf16 v[140:143], v[52:55], v[172:175], v[140:143]
	v_mfma_f32_16x16x32_bf16 v[136:139], v[60:63], v[172:175], v[136:139]
	v_mfma_f32_16x16x32_bf16 v[124:127], v[52:55], v[198:201], v[124:127]
	v_mfma_f32_16x16x32_bf16 v[120:123], v[60:63], v[198:201], v[120:123]
	v_mfma_f32_16x16x32_bf16 v[108:111], v[52:55], v[214:217], v[108:111]
	v_mfma_f32_16x16x32_bf16 v[104:107], v[60:63], v[214:217], v[104:107]
	v_mfma_f32_16x16x32_bf16 v[156:159], v[56:59], v[84:87], v[156:159]
	v_mfma_f32_16x16x32_bf16 v[152:155], v[64:67], v[84:87], v[152:155]
	v_mfma_f32_16x16x32_bf16 v[140:143], v[56:59], v[194:197], v[140:143]
	v_mfma_f32_16x16x32_bf16 v[136:139], v[64:67], v[194:197], v[136:139]
	v_mfma_f32_16x16x32_bf16 v[124:127], v[56:59], v[210:213], v[124:127]
	v_mfma_f32_16x16x32_bf16 v[120:123], v[64:67], v[210:213], v[120:123]
	v_mfma_f32_16x16x32_bf16 v[108:111], v[56:59], v[218:221], v[108:111]
	v_mfma_f32_16x16x32_bf16 v[104:107], v[64:67], v[218:221], v[104:107]
	s_setprio 0
	s_setprio 1
	v_mfma_f32_16x16x32_bf16 v[148:151], v[68:71], v[80:83], v[148:151]
	v_mfma_f32_16x16x32_bf16 v[80:83], v[164:167], v[80:83], v[144:147]
	v_mfma_f32_16x16x32_bf16 v[144:147], v[168:171], v[84:87], v[80:83]
	v_mfma_f32_16x16x32_bf16 v[80:83], v[68:71], v[172:175], v[132:135]
	v_mfma_f32_16x16x32_bf16 v[132:135], v[160:163], v[194:197], v[80:83]
	v_mfma_f32_16x16x32_bf16 v[80:83], v[164:167], v[172:175], v[128:131]
	v_mfma_f32_16x16x32_bf16 v[128:131], v[168:171], v[194:197], v[80:83]
	v_mfma_f32_16x16x32_bf16 v[80:83], v[68:71], v[198:201], v[116:119]
	v_mfma_f32_16x16x32_bf16 v[116:119], v[160:163], v[210:213], v[80:83]
	v_mfma_f32_16x16x32_bf16 v[80:83], v[164:167], v[198:201], v[112:115]
	v_mfma_f32_16x16x32_bf16 v[112:115], v[168:171], v[210:213], v[80:83]
	v_mfma_f32_16x16x32_bf16 v[80:83], v[68:71], v[214:217], v[100:103]
	v_mfma_f32_16x16x32_bf16 v[100:103], v[160:163], v[218:221], v[80:83]
	v_mfma_f32_16x16x32_bf16 v[80:83], v[164:167], v[214:217], v[96:99]
	v_mfma_f32_16x16x32_bf16 v[148:151], v[160:163], v[84:87], v[148:151]
	v_mfma_f32_16x16x32_bf16 v[96:99], v[168:171], v[218:221], v[80:83]
	s_setprio 0
	s_barrier
	s_add_i32 s4, s36, s33
	v_lshl_add_u64 v[84:85], v[228:229], 0, s[50:51]
	s_mov_b32 m0, s4
	s_nop 0
	ds_read_b128 v[80:83], v207 offset:49152
	ds_read_b128 v[172:175], v207 offset:50176
	ds_read_b128 v[194:197], v207 offset:51200
	ds_read_b128 v[198:201], v207 offset:52224
	ds_read_b128 v[210:213], v207 offset:53248
	ds_read_b128 v[214:217], v207 offset:54272
	ds_read_b128 v[218:221], v207 offset:55296
	ds_read_b128 v[224:227], v207 offset:56320
	global_load_lds_dwordx4 v[84:85], off
	s_add_i32 m0, s4, 0x2000
	s_add_u32 s12, s12, 0x40080
	v_lshl_add_u64 v[84:85], v[230:231], 0, s[50:51]
	s_addc_u32 s13, s13, 0
	s_add_i32 s4, s37, s33
	global_load_lds_dwordx4 v[84:85], off
	v_lshl_add_u64 v[84:85], s[12:13], 0, v[178:179]
	s_mov_b32 m0, s4
	s_nop 0
	global_load_lds_dwordx4 v[84:85], off
	v_lshl_add_u64 v[84:85], s[12:13], 0, v[182:183]
	s_add_i32 m0, s4, 0x2000
	s_nop 0
	global_load_lds_dwordx4 v[84:85], off
	v_lshl_add_u64 v[84:85], v[232:233], 0, s[50:51]
	s_mov_b32 m0, s75
	s_nop 0
	global_load_lds_dwordx4 v[84:85], off
	v_lshl_add_u64 v[84:85], v[234:235], 0, s[50:51]
	s_mov_b32 m0, s76
	s_nop 0
	global_load_lds_dwordx4 v[84:85], off
	s_waitcnt vmcnt(8)
	s_waitcnt lgkmcnt(0)
	s_barrier
	s_setprio 1
	s_waitcnt lgkmcnt(0)
	v_mfma_f32_16x16x32_bf16 v[84:87], v[52:55], v[80:83], v[92:95]
	v_mfma_f32_16x16x32_bf16 v[92:95], v[56:59], v[172:175], v[84:87]
	v_mfma_f32_16x16x32_bf16 v[84:87], v[60:63], v[80:83], v[88:91]
	v_mfma_f32_16x16x32_bf16 v[76:79], v[52:55], v[194:197], v[76:79]
	v_mfma_f32_16x16x32_bf16 v[72:75], v[60:63], v[194:197], v[72:75]
	v_mfma_f32_16x16x32_bf16 v[28:31], v[52:55], v[210:213], v[28:31]
	v_mfma_f32_16x16x32_bf16 v[24:27], v[60:63], v[210:213], v[24:27]
	v_mfma_f32_16x16x32_bf16 v[12:15], v[52:55], v[218:221], v[12:15]
	v_mfma_f32_16x16x32_bf16 v[8:11], v[60:63], v[218:221], v[8:11]
	v_mfma_f32_16x16x32_bf16 v[88:91], v[64:67], v[172:175], v[84:87]
	v_mfma_f32_16x16x32_bf16 v[76:79], v[56:59], v[198:201], v[76:79]
	v_mfma_f32_16x16x32_bf16 v[72:75], v[64:67], v[198:201], v[72:75]
	v_mfma_f32_16x16x32_bf16 v[28:31], v[56:59], v[214:217], v[28:31]
	v_mfma_f32_16x16x32_bf16 v[24:27], v[64:67], v[214:217], v[24:27]
	v_mfma_f32_16x16x32_bf16 v[12:15], v[56:59], v[224:227], v[12:15]
	v_mfma_f32_16x16x32_bf16 v[8:11], v[64:67], v[224:227], v[8:11]
	s_setprio 0
	s_setprio 1
	v_mfma_f32_16x16x32_bf16 v[44:47], v[68:71], v[80:83], v[44:47]
	v_mfma_f32_16x16x32_bf16 v[84:87], v[160:163], v[172:175], v[44:47]
	v_mfma_f32_16x16x32_bf16 v[44:47], v[164:167], v[80:83], v[48:51]
	v_mfma_f32_16x16x32_bf16 v[36:39], v[68:71], v[194:197], v[36:39]
	v_mfma_f32_16x16x32_bf16 v[32:35], v[164:167], v[194:197], v[32:35]
	v_mfma_f32_16x16x32_bf16 v[20:23], v[68:71], v[210:213], v[20:23]
	v_mfma_f32_16x16x32_bf16 v[16:19], v[164:167], v[210:213], v[16:19]
	v_mfma_f32_16x16x32_bf16 v[4:7], v[68:71], v[218:221], v[4:7]
	v_mfma_f32_16x16x32_bf16 v[0:3], v[164:167], v[218:221], v[0:3]
	v_mfma_f32_16x16x32_bf16 v[80:83], v[168:171], v[172:175], v[44:47]
	v_mfma_f32_16x16x32_bf16 v[36:39], v[160:163], v[198:201], v[36:39]
	v_mfma_f32_16x16x32_bf16 v[32:35], v[168:171], v[198:201], v[32:35]
	v_mfma_f32_16x16x32_bf16 v[20:23], v[160:163], v[214:217], v[20:23]
	v_mfma_f32_16x16x32_bf16 v[16:19], v[168:171], v[214:217], v[16:19]
	v_mfma_f32_16x16x32_bf16 v[4:7], v[160:163], v[224:227], v[4:7]
	v_mfma_f32_16x16x32_bf16 v[0:3], v[168:171], v[224:227], v[0:3]
	s_setprio 0
	s_barrier
	s_add_i32 s62, s62, 2
	s_add_u32 s8, s8, 0x100
	s_addc_u32 s9, s9, 0
	s_cmp_gt_u32 s62, 13
	s_cbranch_scc0 .LBB0_740
	s_and_b64 vcc, exec, s[52:53]
	s_cbranch_vccz .LBB0_743
	s_barrier
